# mixer P and L stage-in: source-level vmcnt(0) before the stage barrier relaxed to keep the late gate-weight loads in flight (compiler's counted waits cover them)
# speedup vs baseline: 1.0053x; 1.0022x over previous
.LBB0_610:
	s_or_b64 exec, exec, s[26:27]
	v_add_u32_e32 v21, s44, v20
	v_mov_b64_e32 v[34:35], s[6:7]
	v_mad_i64_i32 v[22:23], s[26:27], v21, s3, v[34:35]
	v_add_u32_e32 v26, 16, v21
	v_lshl_add_u64 v[22:23], v[22:23], 0, v[148:149]
	v_mad_i64_i32 v[26:27], s[26:27], v26, s3, v[34:35]
	v_add_u32_e32 v30, 32, v21
	global_load_dwordx4 v[22:25], v[22:23], off offset:2560 nt
	v_lshl_add_u64 v[26:27], v[26:27], 0, v[148:149]
	v_mad_i64_i32 v[30:31], s[26:27], v30, s3, v[34:35]
	v_add_u32_e32 v21, 48, v21
	global_load_dwordx4 v[26:29], v[26:27], off offset:2560 nt
	v_lshl_add_u64 v[30:31], v[30:31], 0, v[148:149]
	v_mad_i64_i32 v[34:35], s[26:27], v21, s3, v[34:35]
	global_load_dwordx4 v[30:33], v[30:31], off offset:2560 nt
	v_lshl_add_u64 v[34:35], v[34:35], 0, v[148:149]
	global_load_dwordx4 v[34:37], v[34:35], off offset:2560 nt
	v_lshlrev_b32_e32 v21, 4, v50
	v_and_b32_e32 v38, 0x1f0, v21
	v_and_b32_e32 v21, 0xfffffe00, v21
	v_readlane_b32 s23, v254, 38
	s_ashr_i32 s42, s45, 1
	s_andn2_b32 s42, s42, 63
	v_add3_u32 v21, s23, v38, v21
	s_movk_i32 s23, 0x210
	s_lshr_b32 s26, s45, 1
	s_waitcnt vmcnt(4)
	ds_write_b128 v21, v[4:7]
	ds_write_b128 v21, v[0:3] offset:8192
	ds_write_b128 v21, v[12:15] offset:16384
	ds_write_b128 v21, v[8:11] offset:24576
	ds_write_b128 v21, v[16:19] offset:32768
	v_mul_lo_u32 v0, v20, s23
	s_add_i32 s23, s42, s24
	s_and_b32 s43, s26, 32
	v_and_b32_e32 v49, 15, v50
	v_add3_u32 v0, 0, v38, v0
	s_or_b32 s23, s23, s43
	v_bfe_u32 v48, v50, 4, 2
	v_readlane_b32 s26, v254, 54
	v_lshlrev_b32_e32 v148, 4, v48
	v_readlane_b32 s27, v254, 55
	s_cmp_lg_u64 s[56:57], 0
	v_cmp_eq_u32_e32 vcc, 0, v50
	v_lshl_add_u64 v[2:3], s[26:27], 0, v[148:149]
	s_cselect_b64 s[26:27], -1, 0
	s_and_b64 s[48:49], s[26:27], vcc
	s_waitcnt vmcnt(3)
	ds_write_b128 v0, v[22:25] offset:33792
	s_waitcnt vmcnt(2)
	ds_write_b128 v0, v[26:29] offset:42240
	s_waitcnt vmcnt(1)
	ds_write_b128 v0, v[30:33] offset:50688
	s_waitcnt vmcnt(0)
	ds_write_b128 v0, v[34:37] offset:59136
	v_or_b32_e32 v0, s23, v49
	v_ashrrev_i32_e32 v1, 31, v0
	v_lshlrev_b64 v[4:5], 7, v[0:1]
	v_or_b32_e32 v0, 16, v0
	v_ashrrev_i32_e32 v1, 31, v0
	v_lshl_add_u64 v[4:5], v[2:3], 0, v[4:5]
	v_lshlrev_b64 v[0:1], 7, v[0:1]
	global_load_dwordx4 v[16:19], v[4:5], off
	global_load_dwordx4 v[20:23], v[4:5], off offset:64
	v_lshl_add_u64 v[4:5], v[2:3], 0, v[0:1]
	global_load_dwordx4 v[0:3], v[4:5], off
	s_nop 0
	global_load_dwordx4 v[4:7], v[4:5], off offset:64
	s_waitcnt vmcnt(4)
	s_waitcnt lgkmcnt(0)
	s_barrier
	s_and_saveexec_b64 s[26:27], s[48:49]
	s_cbranch_execz .LBB0_613
	global_atomic_add v149, v210, s[56:57]
	s_andn2_b64 vcc, exec, s[58:59]
	s_cbranch_vccnz .LBB0_613
	global_atomic_add v149, v210, s[56:57] offset:256

.LBB0_633:
	v_mov_b32_e32 v130, v146
	s_mul_i32 s26, s4, 0x48000
	v_ashrrev_i32_e32 v33, 6, v130
	v_readlane_b32 s43, v254, 46
	v_readfirstlane_b32 s42, v33
	s_mul_hi_i32 s27, s4, 0x48000
	s_add_u32 s26, s43, s26
	v_readlane_b32 s43, v254, 47
	s_addc_u32 s27, s43, s27
	s_mul_i32 s45, s42, 0x7000
	v_readlane_b32 s46, v254, 48
	v_and_b32_e32 v14, 15, v130
	s_mul_hi_i32 s44, s42, 0x7000
	s_add_u32 s45, s46, s45
	v_readlane_b32 s46, v254, 49
	v_bfe_u32 v13, v130, 4, 2
	s_mul_hi_i32 s43, s5, 0x38000
	s_mul_i32 s5, s5, 0x38000
	s_addc_u32 s46, s46, s44
	v_lshl_or_b32 v58, s42, 6, v14
	v_and_b32_e32 v12, 63, v130
	s_add_u32 s44, s45, s5
	v_ashrrev_i32_e32 v59, 31, v58
	v_mad_u32_u24 v16, v13, 9, 1
	v_mad_u32_u24 v17, v13, 9, 2
	v_mad_u32_u24 v18, v13, 9, 3
	s_addc_u32 s45, s46, s43
	v_lshl_add_u64 v[0:1], v[58:59], 3, s[26:27]
	v_cmp_gt_u32_e64 s[42:43], 16, v12
	v_mul_u32_u24_e32 v148, 0x12000, v13
	v_lshlrev_b32_e32 v60, 13, v16
	v_mov_b32_e32 v61, v149
	v_lshlrev_b32_e32 v62, 13, v17
	v_mov_b32_e32 v63, v149
	v_lshlrev_b32_e32 v64, 13, v18
	v_mov_b32_e32 v65, v149
	v_mad_u32_u24 v19, v13, 9, 4
	v_mad_u32_u24 v20, v13, 9, 5
	v_mad_u32_u24 v21, v13, 9, 6
	v_mad_u32_u24 v22, v13, 9, 7
	v_mul_u32_u24_e32 v15, 9, v13
	v_cndmask_b32_e64 v10, 39, 3, s[42:43]
	v_lshl_add_u64 v[2:3], v[0:1], 0, v[148:149]
	v_lshl_add_u64 v[4:5], v[0:1], 0, v[60:61]
	v_lshl_add_u64 v[6:7], v[0:1], 0, v[62:63]
	v_lshl_add_u64 v[8:9], v[0:1], 0, v[64:65]
	v_lshlrev_b32_e32 v66, 13, v19
	v_mov_b32_e32 v67, v149
	v_lshlrev_b32_e32 v68, 13, v20
	v_mov_b32_e32 v69, v149
	v_lshlrev_b32_e32 v74, 13, v21
	v_mov_b32_e32 v75, v149
	v_lshlrev_b32_e32 v80, 13, v22
	v_mov_b32_e32 v81, v149
	global_load_dwordx2 v[70:71], v[2:3], off
	global_load_dwordx2 v[72:73], v[4:5], off
	global_load_dwordx2 v[76:77], v[6:7], off
	global_load_dwordx2 v[78:79], v[8:9], off
	v_lshl_add_u64 v[2:3], v[0:1], 0, v[66:67]
	v_lshl_add_u64 v[4:5], v[0:1], 0, v[68:69]
	v_lshl_add_u64 v[6:7], v[0:1], 0, v[74:75]
	v_lshl_add_u64 v[8:9], v[0:1], 0, v[80:81]
	v_sub_u32_e32 v23, v10, v15
	v_sub_u32_e32 v25, v10, v16
	v_sub_u32_e32 v27, v10, v17
	global_load_dwordx2 v[88:89], v[2:3], off
	global_load_dwordx2 v[90:91], v[4:5], off
	global_load_dwordx2 v[92:93], v[6:7], off
	global_load_dwordx2 v[96:97], v[8:9], off
	v_mad_u32_u24 v24, v13, 9, 8
	v_lshl_or_b32 v4, v23, 1, 1
	v_lshl_or_b32 v6, v25, 1, 1
	v_lshl_or_b32 v8, v27, 1, 1
	v_lshlrev_b32_e32 v82, 13, v24
	v_mov_b32_e32 v83, v149
	v_ashrrev_i32_e32 v5, 31, v4
	v_ashrrev_i32_e32 v7, 31, v6
	v_ashrrev_i32_e32 v9, 31, v8
	v_lshl_add_u64 v[2:3], v[0:1], 0, v[82:83]
	v_lshlrev_b64 v[84:85], 12, v[4:5]
	v_lshlrev_b64 v[86:87], 12, v[6:7]
	v_lshlrev_b64 v[94:95], 12, v[8:9]
	v_sub_u32_e32 v29, v10, v18
	v_lshl_add_u64 v[4:5], v[0:1], 0, v[84:85]
	v_lshl_add_u64 v[6:7], v[0:1], 0, v[86:87]
	v_lshl_add_u64 v[8:9], v[0:1], 0, v[94:95]
	global_load_dwordx2 v[108:109], v[2:3], off
	global_load_dwordx2 v[110:111], v[4:5], off
	global_load_dwordx2 v[114:115], v[6:7], off
	global_load_dwordx2 v[116:117], v[8:9], off
	v_lshl_or_b32 v2, v29, 1, 1
	v_ashrrev_i32_e32 v3, 31, v2
	v_sub_u32_e32 v32, 35, v15
	v_lshlrev_b64 v[98:99], 12, v[2:3]
	v_lshl_or_b32 v100, v32, 13, v216
	v_mov_b32_e32 v101, v149
	v_sub_u32_e32 v26, 34, v15
	v_sub_u32_e32 v28, 33, v15
	v_lshlrev_b32_e32 v38, 4, v12
	v_mov_b32_e32 v39, v149
	v_lshl_add_u64 v[2:3], v[0:1], 0, v[98:99]
	v_lshl_add_u64 v[4:5], v[0:1], 0, v[100:101]
	v_lshl_or_b32 v102, v26, 13, v216
	v_mov_b32_e32 v103, v149
	v_lshl_or_b32 v104, v28, 13, v216
	v_mov_b32_e32 v105, v149
	v_lshl_add_u64 v[56:57], s[44:45], 0, v[38:39]
	v_lshl_add_u64 v[6:7], v[0:1], 0, v[102:103]
	v_lshl_add_u64 v[8:9], v[0:1], 0, v[104:105]
	global_load_dwordx2 v[118:119], v[2:3], off
	global_load_dwordx2 v[120:121], v[4:5], off
	global_load_dwordx2 v[122:123], v[6:7], off
	global_load_dwordx2 v[124:125], v[8:9], off
	s_movk_i32 s5, 0x1000
	v_lshl_add_u32 v40, v33, 3, s23
	v_mov_b64_e32 v[4:5], s[6:7]
	v_add_co_u32_e32 v8, vcc, s5, v56
	v_mad_i64_i32 v[6:7], s[46:47], v40, s3, v[4:5]
	s_nop 0
	v_addc_co_u32_e32 v9, vcc, 0, v57, vcc
	v_lshl_add_u64 v[6:7], v[6:7], 0, v[38:39]
	global_load_dwordx4 v[52:55], v[8:9], off offset:2048 nt
	global_load_dwordx4 v[34:37], v[6:7], off offset:1024 nt
	v_add_u32_e32 v6, 1, v40
	v_mad_i64_i32 v[6:7], s[46:47], v6, s3, v[4:5]
	v_add_u32_e32 v10, 2, v40
	v_lshl_add_u64 v[6:7], v[6:7], 0, v[38:39]
	v_mad_i64_i32 v[10:11], s[46:47], v10, s3, v[4:5]
	v_lshl_add_u64 v[10:11], v[10:11], 0, v[38:39]
	global_load_dwordx4 v[132:135], v[6:7], off offset:1024 nt
	global_load_dwordx4 v[136:139], v[10:11], off offset:1024 nt
	v_add_u32_e32 v6, 3, v40
	v_mad_i64_i32 v[6:7], s[46:47], v6, s3, v[4:5]
	v_add_u32_e32 v10, 4, v40
	v_lshl_add_u64 v[6:7], v[6:7], 0, v[38:39]
	v_mad_i64_i32 v[10:11], s[46:47], v10, s3, v[4:5]
	v_lshl_add_u64 v[10:11], v[10:11], 0, v[38:39]
	global_load_dwordx4 v[140:143], v[6:7], off offset:1024 nt
	global_load_dwordx4 v[156:159], v[10:11], off offset:1024 nt
	v_add_u32_e32 v6, 5, v40
	v_mad_i64_i32 v[6:7], s[46:47], v6, s3, v[4:5]
	v_add_u32_e32 v10, 6, v40
	v_lshl_add_u64 v[6:7], v[6:7], 0, v[38:39]
	v_mad_i64_i32 v[10:11], s[46:47], v10, s3, v[4:5]
	v_sub_u32_e32 v30, 32, v15
	v_xor_b32_e32 v31, 31, v15
	v_lshl_add_u64 v[10:11], v[10:11], 0, v[38:39]
	global_load_dwordx4 v[160:163], v[6:7], off offset:1024 nt
	global_load_dwordx4 v[164:167], v[10:11], off offset:1024 nt
	v_add_u32_e32 v6, 7, v40
	v_lshl_or_b32 v106, v30, 13, v216
	v_mov_b32_e32 v107, v149
	v_lshl_or_b32 v112, v31, 13, v216
	v_mad_i64_i32 v[4:5], s[46:47], v6, s3, v[4:5]
	v_mov_b32_e32 v113, v149
	v_lshl_add_u64 v[2:3], v[0:1], 0, v[106:107]
	v_lshl_add_u64 v[4:5], v[4:5], 0, v[38:39]
	v_lshl_add_u64 v[0:1], v[0:1], 0, v[112:113]
	global_load_dwordx4 v[40:43], v38, s[44:45] nt
	global_load_dwordx4 v[168:171], v[4:5], off offset:1024 nt
	global_load_dwordx2 v[126:127], v[2:3], off
	global_load_dwordx2 v[128:129], v[0:1], off
	s_nop 0
	global_load_dwordx4 v[0:3], v38, s[44:45] offset:1024 nt
	global_load_dwordx4 v[44:47], v38, s[44:45] offset:2048 nt
	global_load_dwordx4 v[4:7], v38, s[44:45] offset:3072 nt
	global_load_dwordx4 v[48:51], v[8:9], off nt
	s_nop 0
	global_load_dwordx4 v[8:11], v[8:9], off offset:1024 nt
	s_movk_i32 s5, 0x2080
	v_mul_lo_u32 v33, v33, s5
	v_readlane_b32 s5, v254, 39
	s_cmp_lg_u64 s[56:57], 0
	s_cselect_b64 s[44:45], -1, 0
	v_add3_u32 v33, s5, v38, v33
	s_waitcnt vmcnt(15)
	ds_write_b128 v33, v[34:37]
	s_waitcnt vmcnt(14)
	ds_write_b128 v33, v[132:135] offset:1040
	s_waitcnt vmcnt(13)
	ds_write_b128 v33, v[136:139] offset:2080
	s_waitcnt vmcnt(12)
	ds_write_b128 v33, v[140:143] offset:3120
	s_waitcnt vmcnt(11)
	ds_write_b128 v33, v[156:159] offset:4160
	s_waitcnt vmcnt(10)
	ds_write_b128 v33, v[160:163] offset:5200
	s_waitcnt vmcnt(9)
	ds_write_b128 v33, v[164:167] offset:6240
	s_waitcnt vmcnt(7)
	ds_write_b128 v33, v[168:171] offset:7280
	s_waitcnt vmcnt(7)
	v_cmp_eq_u32_e32 vcc, 0, v130
	s_and_b64 s[46:47], s[44:45], vcc
	s_waitcnt lgkmcnt(0)
	s_barrier
	s_and_saveexec_b64 s[44:45], s[46:47]
	s_cbranch_execz .LBB0_636
	global_atomic_add v149, v210, s[56:57]
	s_andn2_b64 vcc, exec, s[58:59]
	s_cbranch_vccnz .LBB0_636
	global_atomic_add v149, v210, s[56:57] offset:256
